# attnC loop: K fragments read in batches with counted waits, V fragments pre-read, MFMAs interleaved with softmax VALU
# speedup vs baseline: 1.1487x; 1.0039x over previous
; #define MFMA32(a, b, c) __builtin_amdgcn_mfma_f32_32x32x16_bf16((a), (b), (c), 0, 0, 0)
; DI int crow(int reg, int h) { return (reg & 3) + 8 * (reg >> 2) + 4 * h; }
; template <int MODE>
; DI void attn_mfma(const Params& p, int l, int b, int hd, int qb, unsigned char* smem) {
;     ...
; #pragma unroll
;     for (int ks = 0; ks < KS; ++ks) {
;       const int kk = mp * 2 + ks;
;       const int key0 = r, key1 = 32 + r;
;       const int o0 = key0 * 128 + (((2 * kk + h2) ^ ((key0 >> 1) & 7)) << 4), o1 = key1 * 128 + (((2 * kk + h2) ^ ((key1 >> 1) & 7)) << 4);
;       SA0 = MFMA32(*(const bf16x8*)(sK + o0), qf[ks], SA0);
;       SA1 = MFMA32(*(const bf16x8*)(sK + o1), qf[ks], SA1);
;       SB0 = MFMA32(*(const bf16x8*)(sK + 16896 + o0), qf[ks], SB0);
;       SB1 = MFMA32(*(const bf16x8*)(sK + 16896 + o1), qf[ks], SB1);
;     }
; #pragma unroll
;     for (int hf = 0; hf < 2; ++hf) {
;     const unsigned char* sVc = sV + hf * 16896;
;     const int tbcur = tile_base(j + hf);
;     f32x16 S[2];
;     S[0] = hf == 0 ? SA0 : SB0;
;     S[1] = hf == 0 ? SA1 : SB1;
;     if (MODE == 1 && j + hf >= 4) {
;       const int iq = tq - NCTX;
;       const int jb = tbcur - NCTX;
; #pragma unroll
;       for (int mt = 0; mt < 2; ++mt)
; #pragma unroll
;         for (int i = 0; i < 16; ++i) {
;           const int dd = iq - (jb + mt * 32 + crow(i, h2));
;           if (dd > 128 || dd < -128) S[mt][i] = -1e30f;
;         }
;     }
.LBB0_816:
	s_cmp_gt_u32 s21, 3
	s_cselect_b64 s[8:9], -1, 0
	ds_read_b128 v[220:223], v149
	ds_read_b128 v[224:227], v151
	ds_read_b128 v[228:231], v153
	ds_read_b128 v[232:235], v167
	ds_read_b128 v[236:239], v149 offset:4096
	ds_read_b128 v[240:243], v151 offset:4096
	ds_read_b128 v[244:247], v153 offset:4096
	ds_read_b128 v[248:251], v167 offset:4096
	v_add_u32_e32 v201, s19, v196
	v_add_u32_e32 v202, s13, v197
	v_add_u32_e32 v213, 0x2000, v199
	v_add_u32_e32 v216, 0x3000, v199
	v_add_u32_e32 v217, 0x6000, v199
	v_add_u32_e32 v218, 0x7000, v199
	s_mov_b32 s2, 0xf149f2ca
	s_waitcnt lgkmcnt(6)
	v_mfma_f32_32x32x16_bf16 v[80:95], v[220:223], v[96:99], 0
	v_mfma_f32_32x32x16_bf16 v[80:95], v[224:227], v[100:103], v[80:95]
	ds_read_b128 v[220:223], v149 offset:16896
	ds_read_b128 v[224:227], v151 offset:16896
	s_waitcnt lgkmcnt(6)
	v_mfma_f32_32x32x16_bf16 v[80:95], v[228:231], v[104:107], v[80:95]
	v_mfma_f32_32x32x16_bf16 v[80:95], v[232:235], v[108:111], v[80:95]
	ds_read_b128 v[228:231], v153 offset:16896
	ds_read_b128 v[232:235], v167 offset:16896
	s_waitcnt lgkmcnt(6)
	v_mfma_f32_32x32x16_bf16 v[64:79], v[236:239], v[96:99], 0
	v_mfma_f32_32x32x16_bf16 v[64:79], v[240:243], v[100:103], v[64:79]
	ds_read_b128 v[236:239], v149 offset:20992
	ds_read_b128 v[240:243], v151 offset:20992
	s_waitcnt lgkmcnt(6)
	v_mfma_f32_32x32x16_bf16 v[64:79], v[244:247], v[104:107], v[64:79]
	v_mfma_f32_32x32x16_bf16 v[64:79], v[248:251], v[108:111], v[64:79]
	ds_read_b128 v[244:247], v153 offset:20992
	ds_read_b128 v[248:251], v167 offset:20992
	s_and_b64 vcc, exec, s[8:9]
	s_cbranch_vccz .Lcc_nomaskA
	s_waitcnt lgkmcnt(6)
	v_mfma_f32_32x32x16_bf16 v[48:63], v[220:223], v[96:99], 0
	v_add_u32_e32 v168, 0xffffff7f, v201
	v_cmp_lt_u32_e32 vcc, s25, v168
	v_add_u32_e32 v168, 0x81, v202
	s_nop 0
	v_cndmask_b32_e32 v80, v195, v80, vcc
	v_cmp_gt_u32_e32 vcc, s26, v168
	v_add_u32_e32 v168, 0xffffff7d, v201
	s_nop 0
	v_cndmask_b32_e32 v81, v195, v81, vcc
	v_cmp_lt_u32_e32 vcc, s25, v168
	v_add_u32_e32 v168, 0xffffff7c, v201
	s_nop 0
	v_cndmask_b32_e32 v82, v195, v82, vcc
	v_cmp_lt_u32_e32 vcc, s25, v168
	v_add_u32_e32 v168, 0xffffff77, v201
	s_nop 0
	v_mfma_f32_32x32x16_bf16 v[48:63], v[224:227], v[100:103], v[48:63]
	v_cndmask_b32_e32 v83, v195, v83, vcc
	v_cmp_lt_u32_e32 vcc, s25, v168
	v_add_u32_e32 v168, 0xffffff76, v201
	s_nop 0
	v_cndmask_b32_e32 v84, v195, v84, vcc
	v_cmp_lt_u32_e32 vcc, s25, v168
	v_add_u32_e32 v168, 0xffffff75, v201
	s_nop 0
	v_cndmask_b32_e32 v85, v195, v85, vcc
	v_cmp_lt_u32_e32 vcc, s25, v168
	v_add_u32_e32 v168, 0xffffff74, v201
	s_nop 0
	v_cndmask_b32_e32 v86, v195, v86, vcc
	v_cmp_lt_u32_e32 vcc, s25, v168
	v_add_u32_e32 v168, 0xffffff6f, v201
	s_nop 0
	s_waitcnt lgkmcnt(4)
	v_mfma_f32_32x32x16_bf16 v[48:63], v[228:231], v[104:107], v[48:63]
	v_cndmask_b32_e32 v87, v195, v87, vcc
	v_cmp_lt_u32_e32 vcc, s25, v168
	v_add_u32_e32 v168, 0xffffff6e, v201
	s_nop 0
	v_cndmask_b32_e32 v88, v195, v88, vcc
	v_cmp_lt_u32_e32 vcc, s25, v168
	v_add_u32_e32 v168, 0xffffff6d, v201
	s_nop 0
	v_cndmask_b32_e32 v89, v195, v89, vcc
	v_cmp_lt_u32_e32 vcc, s25, v168
	v_add_u32_e32 v168, 0xffffff6c, v201
	s_nop 0
	v_cndmask_b32_e32 v90, v195, v90, vcc
	v_cmp_lt_u32_e32 vcc, s25, v168
	v_add_u32_e32 v168, 0xffffff67, v201
	s_nop 0
	v_mfma_f32_32x32x16_bf16 v[48:63], v[232:235], v[108:111], v[48:63]
	v_cndmask_b32_e32 v91, v195, v91, vcc
	v_cmp_lt_u32_e32 vcc, s25, v168
	v_add_u32_e32 v168, 0xffffff66, v201
	s_nop 0
	v_cndmask_b32_e32 v92, v195, v92, vcc
	v_cmp_lt_u32_e32 vcc, s25, v168
	v_add_u32_e32 v168, 0xffffff65, v201
	s_nop 0
	v_cndmask_b32_e32 v93, v195, v93, vcc
	v_cmp_lt_u32_e32 vcc, s25, v168
	v_add_u32_e32 v168, 0xffffff64, v201
	s_nop 0
	v_cndmask_b32_e32 v94, v195, v94, vcc
	v_cmp_lt_u32_e32 vcc, s25, v168
	v_add_u32_e32 v168, 0xffffff5f, v201
	s_nop 0
	s_waitcnt lgkmcnt(2)
	v_mfma_f32_32x32x16_bf16 v[32:47], v[236:239], v[96:99], 0
	v_cndmask_b32_e32 v95, v195, v95, vcc
	v_cmp_lt_u32_e32 vcc, s25, v168
	v_add_u32_e32 v168, 0xffffff5e, v201
	s_nop 0
	v_cndmask_b32_e32 v64, v195, v64, vcc
	v_cmp_lt_u32_e32 vcc, s25, v168
	v_add_u32_e32 v168, 0xffffff5d, v201
	s_nop 0
	v_cndmask_b32_e32 v65, v195, v65, vcc
	v_cmp_lt_u32_e32 vcc, s25, v168
	v_add_u32_e32 v168, 0xffffff5c, v201
	s_nop 0
	v_cndmask_b32_e32 v66, v195, v66, vcc
	v_cmp_lt_u32_e32 vcc, s25, v168
	v_add_u32_e32 v168, 0xffffff57, v201
	s_nop 0
	v_mfma_f32_32x32x16_bf16 v[32:47], v[240:243], v[100:103], v[32:47]
	v_cndmask_b32_e32 v67, v195, v67, vcc
	v_cmp_lt_u32_e32 vcc, s25, v168
	v_add_u32_e32 v168, 0xffffff56, v201
	s_nop 0
	v_cndmask_b32_e32 v68, v195, v68, vcc
	v_cmp_lt_u32_e32 vcc, s25, v168
	v_add_u32_e32 v168, 0xffffff55, v201
	s_nop 0
	v_cndmask_b32_e32 v69, v195, v69, vcc
	v_cmp_lt_u32_e32 vcc, s25, v168
	v_add_u32_e32 v168, 0xffffff54, v201
	s_nop 0
	v_cndmask_b32_e32 v70, v195, v70, vcc
	v_cmp_lt_u32_e32 vcc, s25, v168
	v_add_u32_e32 v168, 0xffffff4f, v201
	s_nop 0
	s_waitcnt lgkmcnt(0)
	v_mfma_f32_32x32x16_bf16 v[32:47], v[244:247], v[104:107], v[32:47]
	v_cndmask_b32_e32 v71, v195, v71, vcc
	v_cmp_lt_u32_e32 vcc, s25, v168
	v_add_u32_e32 v168, 0xffffff4e, v201
	s_nop 0
	v_cndmask_b32_e32 v72, v195, v72, vcc
	v_cmp_lt_u32_e32 vcc, s25, v168
	v_add_u32_e32 v168, 0xffffff4d, v201
	s_nop 0
	v_cndmask_b32_e32 v73, v195, v73, vcc
	v_cmp_lt_u32_e32 vcc, s25, v168
	v_add_u32_e32 v168, 0xffffff4c, v201
	s_nop 0
	v_cndmask_b32_e32 v74, v195, v74, vcc
	v_cmp_lt_u32_e32 vcc, s25, v168
	v_add_u32_e32 v168, 0xffffff47, v201
	s_nop 0
	v_mfma_f32_32x32x16_bf16 v[32:47], v[248:251], v[108:111], v[32:47]
	v_cndmask_b32_e32 v75, v195, v75, vcc
	v_cmp_lt_u32_e32 vcc, s25, v168
	v_add_u32_e32 v168, 0xffffff46, v201
	s_nop 0
	v_cndmask_b32_e32 v76, v195, v76, vcc
	v_cmp_lt_u32_e32 vcc, s25, v168
	v_add_u32_e32 v168, 0xffffff45, v201
	s_nop 0
	v_cndmask_b32_e32 v77, v195, v77, vcc
	v_cmp_lt_u32_e32 vcc, s25, v168
	v_add_u32_e32 v168, 0xffffff44, v201
	s_nop 0
	v_cndmask_b32_e32 v78, v195, v78, vcc
	v_cmp_lt_u32_e32 vcc, s25, v168
	s_nop 1
	v_cndmask_b32_e32 v79, v195, v79, vcc
	s_branch .Lcc_qkdone
; DI unsigned pk2(float a, float b) { hwf32x2 f = {a, b}; hwbf16x2 r = __builtin_convertvector(f, hwbf16x2); return __builtin_bit_cast(unsigned, r); }
; #define MFMA32(a, b, c) __builtin_amdgcn_mfma_f32_32x32x16_bf16((a), (b), (c), 0, 0, 0)
; template <int MODE>
; DI void attn_mfma(const Params& p, int l, int b, int hd, int qb, unsigned char* smem) {
;     ...
;     float mx = -1e30f;
; #pragma unroll
;     for (int mt = 0; mt < 2; ++mt)
; #pragma unroll
;       for (int i = 0; i < 16; ++i) mx = fmaxf(mx, S[mt][i]);
;     mx = fmaxf(mx, __shfl_xor(mx, 32));
;     const float zmx = mx * cexp;
;     if (__any(zmx > mrun + 8.f)) {
;       const float mnew = fmaxf(mrun, zmx);
;       const float alpha = __builtin_amdgcn_exp2f(mrun - mnew);
;       mrun = mnew;
;       lsum *= alpha;
;       const f32x2 al2 = {alpha, alpha};
; #pragma unroll
;       for (int vt = 0; vt < 2; ++vt)
; #pragma unroll
;         for (int i = 0; i < 8; ++i) {
;           f32x2 o = {O[vt][2 * i], O[vt][2 * i + 1]};
;           o = o * al2;
;           O[vt][2 * i] = o.x; O[vt][2 * i + 1] = o.y;
;         }
;     }
;     const f32x2 c2 = {cexp, cexp}, m2 = {mrun, mrun};
;     f32x2 ps2 = {0.f, 0.f};
;     unsigned pk[2][8];
; #pragma unroll
;     for (int mt = 0; mt < 2; ++mt)
; #pragma unroll
;       for (int i = 0; i < 8; ++i) {
;         f32x2 z = {S[mt][2 * i], S[mt][2 * i + 1]};
;         z = z * c2 - m2;
;         f32x2 pv = {__builtin_amdgcn_exp2f(z.x), __builtin_amdgcn_exp2f(z.y)};
;         ps2 = ps2 + pv;
;         pk[mt][i] = pk2(pv.x, pv.y);
;       }
;     lsum += ps2.x + ps2.y;
; #pragma unroll
;     for (int mt = 0; mt < 2; ++mt)
; #pragma unroll
;       for (int s = 0; s < 2; ++s) {
;         const uint4 pu = make_uint4(pk[mt][4 * s], pk[mt][4 * s + 1], pk[mt][4 * s + 2], pk[mt][4 * s + 3]);
;         const bf16x8 pf = __builtin_bit_cast(bf16x8, pu);
; #pragma unroll
;         for (int vt = 0; vt < 2; ++vt) {
;           const unsigned char* bp = sVc + (vt * 32 + r) * 136 + (mt * 32 + 16 * s + 4 * h2) * 2;
;           const uint2 lo = *(const uint2*)(bp);
;           const uint2 hi = *(const uint2*)(bp + 16);
;           const uint4 u = make_uint4(lo.x, lo.y, hi.x, hi.y);
;           O[vt] = MFMA32(__builtin_bit_cast(bf16x8, u), pf, O[vt]);
;         }
;       }
.Lcc_nomaskA:
	s_waitcnt lgkmcnt(6)
	v_mfma_f32_32x32x16_bf16 v[48:63], v[220:223], v[96:99], 0
	v_mfma_f32_32x32x16_bf16 v[48:63], v[224:227], v[100:103], v[48:63]
	s_waitcnt lgkmcnt(4)
	v_mfma_f32_32x32x16_bf16 v[48:63], v[228:231], v[104:107], v[48:63]
	v_mfma_f32_32x32x16_bf16 v[48:63], v[232:235], v[108:111], v[48:63]
	s_waitcnt lgkmcnt(2)
	v_mfma_f32_32x32x16_bf16 v[32:47], v[236:239], v[96:99], 0
	v_mfma_f32_32x32x16_bf16 v[32:47], v[240:243], v[100:103], v[32:47]
	s_waitcnt lgkmcnt(0)
	v_mfma_f32_32x32x16_bf16 v[32:47], v[244:247], v[104:107], v[32:47]
	v_mfma_f32_32x32x16_bf16 v[32:47], v[248:251], v[108:111], v[32:47]
.Lcc_qkdone:
	ds_read2_b64 v[220:223], v213 offset1:2
	ds_read2_b64 v[224:227], v216 offset0:32 offset1:34
	ds_read2_b64 v[228:231], v213 offset0:4 offset1:6
	ds_read2_b64 v[232:235], v216 offset0:36 offset1:38
	ds_read2_b64 v[236:239], v213 offset0:8 offset1:10
	ds_read2_b64 v[240:243], v216 offset0:40 offset1:42
	ds_read2_b64 v[244:247], v213 offset0:12 offset1:14
	ds_read2_b64 v[248:251], v216 offset0:44 offset1:46
	v_max3_f32 v204, v80, s2, v81
	v_max3_f32 v204, v204, v82, v83
	v_max3_f32 v204, v204, v84, v85
	v_max3_f32 v204, v204, v86, v87
	v_max3_f32 v204, v204, v88, v89
	v_max3_f32 v204, v204, v90, v91
	v_max3_f32 v204, v204, v92, v93
	v_max3_f32 v204, v204, v94, v95
	v_max3_f32 v204, v204, v64, v65
	v_max3_f32 v204, v204, v66, v67
	v_max3_f32 v204, v204, v68, v69
	v_max3_f32 v204, v204, v70, v71
	v_max3_f32 v204, v204, v72, v73
	v_max3_f32 v204, v204, v74, v75
	v_max3_f32 v204, v204, v76, v77
	v_max3_f32 v204, v204, v78, v79
	ds_bpermute_b32 v205, v145, v204
	s_waitcnt lgkmcnt(0)
	v_max_f32_e32 v205, v205, v205
	v_max_f32_e32 v204, v204, v205
	v_mul_f32_e32 v204, 0x3e38aa3b, v204
	v_add_f32_e32 v206, 0x41000000, v166
	v_cmp_gt_f32_e32 vcc, v204, v206
	s_cbranch_vccz .Lcc_nra
	v_max_f32_e32 v204, v204, v204
	v_max_f32_e32 v205, v166, v166
	v_max_f32_e32 v204, v205, v204
	v_sub_f32_e32 v166, v166, v204
	v_exp_f32_e32 v166, v166
	s_nop 0
	v_pk_mul_f32 v[18:19], v[18:19], v[166:167] op_sel_hi:[1,0]
	v_pk_mul_f32 v[20:21], v[20:21], v[166:167] op_sel_hi:[1,0]
	v_pk_mul_f32 v[22:23], v[22:23], v[166:167] op_sel_hi:[1,0]
	v_pk_mul_f32 v[24:25], v[24:25], v[166:167] op_sel_hi:[1,0]
	v_pk_mul_f32 v[26:27], v[26:27], v[166:167] op_sel_hi:[1,0]
	v_pk_mul_f32 v[28:29], v[28:29], v[166:167] op_sel_hi:[1,0]
	v_pk_mul_f32 v[16:17], v[16:17], v[166:167] op_sel_hi:[1,0]
	v_pk_mul_f32 v[30:31], v[30:31], v[166:167] op_sel_hi:[1,0]
	v_pk_mul_f32 v[0:1], v[0:1], v[166:167] op_sel_hi:[1,0]
	v_pk_mul_f32 v[2:3], v[2:3], v[166:167] op_sel_hi:[1,0]
	v_pk_mul_f32 v[4:5], v[4:5], v[166:167] op_sel_hi:[1,0]
	v_pk_mul_f32 v[6:7], v[6:7], v[166:167] op_sel_hi:[1,0]
	v_pk_mul_f32 v[8:9], v[8:9], v[166:167] op_sel_hi:[1,0]
	v_pk_mul_f32 v[10:11], v[10:11], v[166:167] op_sel_hi:[1,0]
	v_pk_mul_f32 v[12:13], v[12:13], v[166:167] op_sel_hi:[1,0]
	v_pk_mul_f32 v[14:15], v[14:15], v[166:167] op_sel_hi:[1,0]
	v_mul_f32_e32 v200, v200, v166
	v_mov_b32_e32 v166, v204
.Lcc_nra:
	v_fma_f32 v80, v80, s28, -v166
	v_fma_f32 v81, v81, s28, -v166
	v_fma_f32 v82, v82, s28, -v166
	v_fma_f32 v83, v83, s28, -v166
	v_fma_f32 v84, v84, s28, -v166
	v_fma_f32 v85, v85, s28, -v166
	v_fma_f32 v86, v86, s28, -v166
	v_fma_f32 v87, v87, s28, -v166
	v_exp_f32_e32 v80, v80
	v_exp_f32_e32 v81, v81
	v_exp_f32_e32 v82, v82
	v_exp_f32_e32 v83, v83
	v_exp_f32_e32 v84, v84
	v_exp_f32_e32 v85, v85
	v_exp_f32_e32 v86, v86
	v_exp_f32_e32 v87, v87
	v_add_f32_e64 v208, v80, 0
	v_add_f32_e64 v209, v81, 0
	v_add_f32_e32 v208, v82, v208
	v_add_f32_e32 v209, v83, v209
	v_add_f32_e32 v208, v84, v208
	v_add_f32_e32 v209, v85, v209
	v_add_f32_e32 v208, v86, v208
	v_add_f32_e32 v209, v87, v209
	v_cvt_pk_bf16_f32 v80, v80, v81
	v_cvt_pk_bf16_f32 v81, v82, v83
	v_cvt_pk_bf16_f32 v82, v84, v85
	v_cvt_pk_bf16_f32 v83, v86, v87
	v_fma_f32 v88, v88, s28, -v166
	v_fma_f32 v89, v89, s28, -v166
	v_fma_f32 v90, v90, s28, -v166
	v_mfma_f32_32x32x16_bf16 v[16:31], v[220:223], v[80:83], v[16:31]
	v_fma_f32 v91, v91, s28, -v166
	v_fma_f32 v92, v92, s28, -v166
	v_fma_f32 v93, v93, s28, -v166
	v_fma_f32 v94, v94, s28, -v166
	v_fma_f32 v95, v95, s28, -v166
	v_exp_f32_e32 v88, v88
	v_exp_f32_e32 v89, v89
	v_exp_f32_e32 v90, v90
	v_exp_f32_e32 v91, v91
	v_exp_f32_e32 v92, v92
	v_exp_f32_e32 v93, v93
	v_exp_f32_e32 v94, v94
	v_mfma_f32_32x32x16_bf16 v[0:15], v[224:227], v[80:83], v[0:15]
	v_exp_f32_e32 v95, v95
	v_add_f32_e32 v208, v88, v208
	v_add_f32_e32 v209, v89, v209
	v_add_f32_e32 v208, v90, v208
	v_add_f32_e32 v209, v91, v209
	v_add_f32_e32 v208, v92, v208
	v_add_f32_e32 v209, v93, v209
	v_add_f32_e32 v208, v94, v208
	v_add_f32_e32 v209, v95, v209
	v_cvt_pk_bf16_f32 v88, v88, v89
	v_cvt_pk_bf16_f32 v89, v90, v91
	v_cvt_pk_bf16_f32 v90, v92, v93
	v_cvt_pk_bf16_f32 v91, v94, v95
	v_fma_f32 v64, v64, s28, -v166
	v_fma_f32 v65, v65, s28, -v166
	v_fma_f32 v66, v66, s28, -v166
	v_mfma_f32_32x32x16_bf16 v[16:31], v[228:231], v[88:91], v[16:31]
	v_fma_f32 v67, v67, s28, -v166
	v_fma_f32 v68, v68, s28, -v166
	v_fma_f32 v69, v69, s28, -v166
	v_fma_f32 v70, v70, s28, -v166
	v_fma_f32 v71, v71, s28, -v166
	v_exp_f32_e32 v64, v64
	v_exp_f32_e32 v65, v65
	v_exp_f32_e32 v66, v66
	v_exp_f32_e32 v67, v67
	v_exp_f32_e32 v68, v68
	v_exp_f32_e32 v69, v69
	v_exp_f32_e32 v70, v70
	v_mfma_f32_32x32x16_bf16 v[0:15], v[232:235], v[88:91], v[0:15]
	v_exp_f32_e32 v71, v71
	v_add_f32_e32 v208, v64, v208
	v_add_f32_e32 v209, v65, v209
	v_add_f32_e32 v208, v66, v208
	v_add_f32_e32 v209, v67, v209
	v_add_f32_e32 v208, v68, v208
	v_add_f32_e32 v209, v69, v209
	v_add_f32_e32 v208, v70, v208
	v_add_f32_e32 v209, v71, v209
	v_cvt_pk_bf16_f32 v84, v64, v65
	v_cvt_pk_bf16_f32 v85, v66, v67
	v_cvt_pk_bf16_f32 v86, v68, v69
	v_cvt_pk_bf16_f32 v87, v70, v71
	v_fma_f32 v72, v72, s28, -v166
	v_fma_f32 v73, v73, s28, -v166
	v_fma_f32 v74, v74, s28, -v166
	v_mfma_f32_32x32x16_bf16 v[16:31], v[236:239], v[84:87], v[16:31]
	v_fma_f32 v75, v75, s28, -v166
	v_fma_f32 v76, v76, s28, -v166
	v_fma_f32 v77, v77, s28, -v166
	v_fma_f32 v78, v78, s28, -v166
	v_fma_f32 v79, v79, s28, -v166
	v_exp_f32_e32 v72, v72
	v_exp_f32_e32 v73, v73
	v_exp_f32_e32 v74, v74
	v_exp_f32_e32 v75, v75
	v_exp_f32_e32 v76, v76
	v_exp_f32_e32 v77, v77
	v_exp_f32_e32 v78, v78
	v_mfma_f32_32x32x16_bf16 v[0:15], v[240:243], v[84:87], v[0:15]
	v_exp_f32_e32 v79, v79
	v_add_f32_e32 v208, v72, v208
	v_add_f32_e32 v209, v73, v209
	v_add_f32_e32 v208, v74, v208
	v_add_f32_e32 v209, v75, v209
	v_add_f32_e32 v208, v76, v208
	v_add_f32_e32 v209, v77, v209
	v_add_f32_e32 v208, v78, v208
	v_add_f32_e32 v209, v79, v209
	v_cvt_pk_bf16_f32 v64, v72, v73
	v_cvt_pk_bf16_f32 v65, v74, v75
	v_cvt_pk_bf16_f32 v66, v76, v77
	v_cvt_pk_bf16_f32 v67, v78, v79
	v_add_f32_e32 v211, v208, v209
	v_add_f32_e32 v212, v200, v211
	v_mfma_f32_32x32x16_bf16 v[16:31], v[244:247], v[64:67], v[16:31]
	s_and_b64 vcc, exec, s[8:9]
	s_cbranch_vccz .Lcc_nomaskB
; DI int crow(int reg, int h) { return (reg & 3) + 8 * (reg >> 2) + 4 * h; }
; template <int MODE>
; DI void attn_mfma(const Params& p, int l, int b, int hd, int qb, unsigned char* smem) {
;     ...
;     if (MODE == 1 && j + hf >= 4) {
;       const int iq = tq - NCTX;
;       const int jb = tbcur - NCTX;
; #pragma unroll
;       for (int mt = 0; mt < 2; ++mt)
; #pragma unroll
;         for (int i = 0; i < 16; ++i) {
;           const int dd = iq - (jb + mt * 32 + crow(i, h2));
;           if (dd > 128 || dd < -128) S[mt][i] = -1e30f;
;         }
;     }
;     float mx = -1e30f;
; #pragma unroll
;     for (int mt = 0; mt < 2; ++mt)
; #pragma unroll
;       for (int i = 0; i < 16; ++i) mx = fmaxf(mx, S[mt][i]);
;     mx = fmaxf(mx, __shfl_xor(mx, 32));
;     const float zmx = mx * cexp;
;     if (__any(zmx > mrun + 8.f)) {
;       const float mnew = fmaxf(mrun, zmx);
;       const float alpha = __builtin_amdgcn_exp2f(mrun - mnew);
;       mrun = mnew;
;       lsum *= alpha;
;       const f32x2 al2 = {alpha, alpha};
; #pragma unroll
;       for (int vt = 0; vt < 2; ++vt)
; #pragma unroll
;         for (int i = 0; i < 8; ++i) {
;           f32x2 o = {O[vt][2 * i], O[vt][2 * i + 1]};
;           o = o * al2;
;           O[vt][2 * i] = o.x; O[vt][2 * i + 1] = o.y;
;         }
;     }
	v_add_u32_e32 v168, 0xffffff3f, v201
	v_cmp_lt_u32_e32 vcc, s25, v168
	v_add_u32_e32 v168, 0xc1, v202
	s_nop 0
	v_cndmask_b32_e32 v48, v195, v48, vcc
	v_cmp_gt_u32_e32 vcc, s26, v168
	v_add_u32_e32 v168, 0xffffff3d, v201
	s_nop 0
	v_cndmask_b32_e32 v49, v195, v49, vcc
	v_cmp_lt_u32_e32 vcc, s25, v168
	v_add_u32_e32 v168, 0xffffff3c, v201
	s_nop 0
	v_cndmask_b32_e32 v50, v195, v50, vcc
	v_cmp_lt_u32_e32 vcc, s25, v168
	v_add_u32_e32 v168, 0xffffff37, v201
	s_nop 0
	v_cndmask_b32_e32 v51, v195, v51, vcc
	v_cmp_lt_u32_e32 vcc, s25, v168
	v_add_u32_e32 v168, 0xffffff36, v201
	s_nop 0
	v_cndmask_b32_e32 v52, v195, v52, vcc
	v_cmp_lt_u32_e32 vcc, s25, v168
	v_add_u32_e32 v168, 0xffffff35, v201
	s_nop 0
	v_cndmask_b32_e32 v53, v195, v53, vcc
	v_cmp_lt_u32_e32 vcc, s25, v168
	v_add_u32_e32 v168, 0xffffff34, v201
	s_nop 0
	v_cndmask_b32_e32 v54, v195, v54, vcc
	v_cmp_lt_u32_e32 vcc, s25, v168
	v_add_u32_e32 v168, 0xffffff2f, v201
	s_nop 0
	v_cndmask_b32_e32 v55, v195, v55, vcc
	v_cmp_lt_u32_e32 vcc, s25, v168
	v_add_u32_e32 v168, 0xffffff2e, v201
	s_nop 0
	v_cndmask_b32_e32 v56, v195, v56, vcc
	v_cmp_lt_u32_e32 vcc, s25, v168
	v_add_u32_e32 v168, 0xffffff2d, v201
	s_nop 0
	v_cndmask_b32_e32 v57, v195, v57, vcc
	v_cmp_lt_u32_e32 vcc, s25, v168
	v_add_u32_e32 v168, 0xffffff2c, v201
	s_nop 0
	v_cndmask_b32_e32 v58, v195, v58, vcc
	v_cmp_lt_u32_e32 vcc, s25, v168
	v_add_u32_e32 v168, 0xffffff27, v201
	s_nop 0
	v_cndmask_b32_e32 v59, v195, v59, vcc
	v_cmp_lt_u32_e32 vcc, s25, v168
	v_add_u32_e32 v168, 0xffffff26, v201
	s_nop 0
	v_cndmask_b32_e32 v60, v195, v60, vcc
	v_cmp_lt_u32_e32 vcc, s25, v168
	v_add_u32_e32 v168, 0xffffff25, v201
	s_nop 0
	v_cndmask_b32_e32 v61, v195, v61, vcc
	v_cmp_lt_u32_e32 vcc, s25, v168
	v_add_u32_e32 v168, 0xffffff24, v201
	s_nop 0
	v_cndmask_b32_e32 v62, v195, v62, vcc
	v_cmp_lt_u32_e32 vcc, s25, v168
	v_add_u32_e32 v168, 0xffffff1f, v201
	s_nop 0
	v_cndmask_b32_e32 v63, v195, v63, vcc
	v_cmp_lt_u32_e32 vcc, s25, v168
	v_add_u32_e32 v168, 0xffffff1e, v201
	s_nop 0
	v_cndmask_b32_e32 v32, v195, v32, vcc
	v_cmp_lt_u32_e32 vcc, s25, v168
	v_add_u32_e32 v168, 0xffffff1d, v201
	s_nop 0
	v_cndmask_b32_e32 v33, v195, v33, vcc
	v_cmp_lt_u32_e32 vcc, s25, v168
	v_add_u32_e32 v168, 0xffffff1c, v201
	s_nop 0
	v_cndmask_b32_e32 v34, v195, v34, vcc
	v_cmp_lt_u32_e32 vcc, s25, v168
	v_add_u32_e32 v168, 0xffffff17, v201
	s_nop 0
	v_cndmask_b32_e32 v35, v195, v35, vcc
	v_cmp_lt_u32_e32 vcc, s25, v168
	v_add_u32_e32 v168, 0xffffff16, v201
	s_nop 0
	v_cndmask_b32_e32 v36, v195, v36, vcc
	v_cmp_lt_u32_e32 vcc, s25, v168
	v_add_u32_e32 v168, 0xffffff15, v201
	s_nop 0
	v_cndmask_b32_e32 v37, v195, v37, vcc
	v_cmp_lt_u32_e32 vcc, s25, v168
	v_add_u32_e32 v168, 0xffffff14, v201
	s_nop 0
	v_cndmask_b32_e32 v38, v195, v38, vcc
	v_cmp_lt_u32_e32 vcc, s25, v168
	v_add_u32_e32 v168, 0xffffff0f, v201
	s_nop 0
	v_cndmask_b32_e32 v39, v195, v39, vcc
	v_cmp_lt_u32_e32 vcc, s25, v168
	v_add_u32_e32 v168, 0xffffff0e, v201
	s_nop 0
	v_cndmask_b32_e32 v40, v195, v40, vcc
	v_cmp_lt_u32_e32 vcc, s25, v168
	v_add_u32_e32 v168, 0xffffff0d, v201
	s_nop 0
	v_cndmask_b32_e32 v41, v195, v41, vcc
	v_cmp_lt_u32_e32 vcc, s25, v168
	v_add_u32_e32 v168, 0xffffff0c, v201
	s_nop 0
	v_cndmask_b32_e32 v42, v195, v42, vcc
	v_cmp_lt_u32_e32 vcc, s25, v168
	v_add_u32_e32 v168, 0xffffff07, v201
	s_nop 0
	v_cndmask_b32_e32 v43, v195, v43, vcc
	v_cmp_lt_u32_e32 vcc, s25, v168
	v_add_u32_e32 v168, 0xffffff06, v201
	s_nop 0
	v_cndmask_b32_e32 v44, v195, v44, vcc
	v_cmp_lt_u32_e32 vcc, s25, v168
	v_add_u32_e32 v168, 0xffffff05, v201
	s_nop 0
	v_cndmask_b32_e32 v45, v195, v45, vcc
	v_cmp_lt_u32_e32 vcc, s25, v168
	v_add_u32_e32 v168, 0xffffff04, v201
	s_nop 0
	v_cndmask_b32_e32 v46, v195, v46, vcc
	v_cmp_lt_u32_e32 vcc, s25, v168
	s_nop 1
	v_cndmask_b32_e32 v47, v195, v47, vcc
.Lcc_nomaskB:
	v_max3_f32 v210, v48, s2, v49
	v_max3_f32 v210, v210, v50, v51
	v_max3_f32 v210, v210, v52, v53
	v_max3_f32 v210, v210, v54, v55
	v_max3_f32 v210, v210, v56, v57
	v_max3_f32 v210, v210, v58, v59
	v_max3_f32 v210, v210, v60, v61
	v_max3_f32 v210, v210, v62, v63
	v_mfma_f32_32x32x16_bf16 v[0:15], v[248:251], v[64:67], v[0:15]
	v_max3_f32 v210, v210, v32, v33
	v_max3_f32 v210, v210, v34, v35
	v_max3_f32 v210, v210, v36, v37
	v_max3_f32 v210, v210, v38, v39
	v_max3_f32 v210, v210, v40, v41
	v_max3_f32 v210, v210, v42, v43
	v_max3_f32 v210, v210, v44, v45
	v_max3_f32 v210, v210, v46, v47
	ds_bpermute_b32 v211, v145, v210
	ds_read2_b64 v[220:223], v217 offset0:64 offset1:66
	ds_read2_b64 v[224:227], v218 offset0:96 offset1:98
	ds_read2_b64 v[228:231], v217 offset0:68 offset1:70
	ds_read2_b64 v[232:235], v218 offset0:100 offset1:102
	ds_read2_b64 v[236:239], v217 offset0:72 offset1:74
	ds_read2_b64 v[240:243], v218 offset0:104 offset1:106
	ds_read2_b64 v[244:247], v217 offset0:76 offset1:78
	ds_read2_b64 v[248:251], v218 offset0:108 offset1:110
	s_waitcnt lgkmcnt(8)
	v_max_f32_e32 v211, v211, v211
	v_max_f32_e32 v210, v210, v211
	v_mul_f32_e32 v210, 0x3e38aa3b, v210
	v_add_f32_e32 v211, 0x41000000, v166
	v_cmp_gt_f32_e32 vcc, v210, v211
	s_cbranch_vccz .Lcc_nrb
	v_max_f32_e32 v210, v210, v210
	v_max_f32_e32 v211, v166, v166
	v_max_f32_e32 v210, v211, v210
	v_sub_f32_e32 v211, v166, v210
	v_exp_f32_e32 v214, v211
	v_mov_b32_e32 v166, v210
	v_pk_mul_f32 v[16:17], v[16:17], v[214:215] op_sel_hi:[1,0]
	v_pk_mul_f32 v[18:19], v[18:19], v[214:215] op_sel_hi:[1,0]
	v_pk_mul_f32 v[20:21], v[20:21], v[214:215] op_sel_hi:[1,0]
	v_pk_mul_f32 v[22:23], v[22:23], v[214:215] op_sel_hi:[1,0]
	v_pk_mul_f32 v[24:25], v[24:25], v[214:215] op_sel_hi:[1,0]
	v_pk_mul_f32 v[26:27], v[26:27], v[214:215] op_sel_hi:[1,0]
	v_pk_mul_f32 v[28:29], v[28:29], v[214:215] op_sel_hi:[1,0]
	v_pk_mul_f32 v[30:31], v[30:31], v[214:215] op_sel_hi:[1,0]
	v_pk_mul_f32 v[0:1], v[0:1], v[214:215] op_sel_hi:[1,0]
	v_pk_mul_f32 v[2:3], v[2:3], v[214:215] op_sel_hi:[1,0]
	v_pk_mul_f32 v[4:5], v[4:5], v[214:215] op_sel_hi:[1,0]
	v_pk_mul_f32 v[6:7], v[6:7], v[214:215] op_sel_hi:[1,0]
	v_pk_mul_f32 v[8:9], v[8:9], v[214:215] op_sel_hi:[1,0]
	v_pk_mul_f32 v[10:11], v[10:11], v[214:215] op_sel_hi:[1,0]
	v_pk_mul_f32 v[12:13], v[12:13], v[214:215] op_sel_hi:[1,0]
	v_pk_mul_f32 v[14:15], v[14:15], v[214:215] op_sel_hi:[1,0]
	v_mul_f32_e32 v212, v212, v214
; DI unsigned pk2(float a, float b) { hwf32x2 f = {a, b}; hwbf16x2 r = __builtin_convertvector(f, hwbf16x2); return __builtin_bit_cast(unsigned, r); }
; #define MFMA32(a, b, c) __builtin_amdgcn_mfma_f32_32x32x16_bf16((a), (b), (c), 0, 0, 0)
; template <int MODE>
; DI void attn_mfma(const Params& p, int l, int b, int hd, int qb, unsigned char* smem) {
;     ...
;     const f32x2 c2 = {cexp, cexp}, m2 = {mrun, mrun};
;     f32x2 ps2 = {0.f, 0.f};
;     unsigned pk[2][8];
; #pragma unroll
;     for (int mt = 0; mt < 2; ++mt)
; #pragma unroll
;       for (int i = 0; i < 8; ++i) {
;         f32x2 z = {S[mt][2 * i], S[mt][2 * i + 1]};
;         z = z * c2 - m2;
;         f32x2 pv = {__builtin_amdgcn_exp2f(z.x), __builtin_amdgcn_exp2f(z.y)};
;         ps2 = ps2 + pv;
;         pk[mt][i] = pk2(pv.x, pv.y);
;       }
;     lsum += ps2.x + ps2.y;
; #pragma unroll
;     for (int mt = 0; mt < 2; ++mt)
; #pragma unroll
;       for (int s = 0; s < 2; ++s) {
;         const uint4 pu = make_uint4(pk[mt][4 * s], pk[mt][4 * s + 1], pk[mt][4 * s + 2], pk[mt][4 * s + 3]);
;         const bf16x8 pf = __builtin_bit_cast(bf16x8, pu);
; #pragma unroll
;         for (int vt = 0; vt < 2; ++vt) {
;           const unsigned char* bp = sVc + (vt * 32 + r) * 136 + (mt * 32 + 16 * s + 4 * h2) * 2;
;           const uint2 lo = *(const uint2*)(bp);
;           const uint2 hi = *(const uint2*)(bp + 16);
;           const uint4 u = make_uint4(lo.x, lo.y, hi.x, hi.y);
;           O[vt] = MFMA32(__builtin_bit_cast(bf16x8, u), pf, O[vt]);
;         }
;       }
;     }
;   }
.Lcc_nrb:
	v_fma_f32 v48, v48, s28, -v166
	v_fma_f32 v49, v49, s28, -v166
	v_fma_f32 v50, v50, s28, -v166
	v_fma_f32 v51, v51, s28, -v166
	v_fma_f32 v52, v52, s28, -v166
	v_fma_f32 v53, v53, s28, -v166
	v_fma_f32 v54, v54, s28, -v166
	v_fma_f32 v55, v55, s28, -v166
	v_exp_f32_e32 v48, v48
	v_exp_f32_e32 v49, v49
	v_exp_f32_e32 v50, v50
	v_exp_f32_e32 v51, v51
	v_exp_f32_e32 v52, v52
	v_exp_f32_e32 v53, v53
	v_exp_f32_e32 v54, v54
	v_exp_f32_e32 v55, v55
	v_add_f32_e64 v208, v48, 0
	v_add_f32_e64 v209, v49, 0
	v_add_f32_e32 v208, v50, v208
	v_add_f32_e32 v209, v51, v209
	v_add_f32_e32 v208, v52, v208
	v_add_f32_e32 v209, v53, v209
	v_add_f32_e32 v208, v54, v208
	v_add_f32_e32 v209, v55, v209
	v_cvt_pk_bf16_f32 v48, v48, v49
	v_cvt_pk_bf16_f32 v49, v50, v51
	v_cvt_pk_bf16_f32 v50, v52, v53
	v_cvt_pk_bf16_f32 v51, v54, v55
	v_fma_f32 v56, v56, s28, -v166
	v_fma_f32 v57, v57, s28, -v166
	v_fma_f32 v58, v58, s28, -v166
	s_waitcnt lgkmcnt(4)
	v_mfma_f32_32x32x16_bf16 v[16:31], v[220:223], v[48:51], v[16:31]
	v_fma_f32 v59, v59, s28, -v166
	v_fma_f32 v60, v60, s28, -v166
	v_fma_f32 v61, v61, s28, -v166
	v_fma_f32 v62, v62, s28, -v166
	v_fma_f32 v63, v63, s28, -v166
	v_exp_f32_e32 v56, v56
	v_exp_f32_e32 v57, v57
	v_exp_f32_e32 v58, v58
	v_exp_f32_e32 v59, v59
	v_exp_f32_e32 v60, v60
	v_exp_f32_e32 v61, v61
	v_exp_f32_e32 v62, v62
	v_mfma_f32_32x32x16_bf16 v[0:15], v[224:227], v[48:51], v[0:15]
	v_exp_f32_e32 v63, v63
	v_add_f32_e32 v208, v56, v208
	v_add_f32_e32 v209, v57, v209
	v_add_f32_e32 v208, v58, v208
	v_add_f32_e32 v209, v59, v209
	v_add_f32_e32 v208, v60, v208
	v_add_f32_e32 v209, v61, v209
	v_add_f32_e32 v208, v62, v208
	v_add_f32_e32 v209, v63, v209
	v_cvt_pk_bf16_f32 v56, v56, v57
	v_cvt_pk_bf16_f32 v57, v58, v59
	v_cvt_pk_bf16_f32 v58, v60, v61
	v_cvt_pk_bf16_f32 v59, v62, v63
	v_fma_f32 v32, v32, s28, -v166
	v_fma_f32 v33, v33, s28, -v166
	v_fma_f32 v34, v34, s28, -v166
	v_mfma_f32_32x32x16_bf16 v[16:31], v[228:231], v[56:59], v[16:31]
	v_fma_f32 v35, v35, s28, -v166
	v_fma_f32 v36, v36, s28, -v166
	v_fma_f32 v37, v37, s28, -v166
	v_fma_f32 v38, v38, s28, -v166
	v_fma_f32 v39, v39, s28, -v166
	v_exp_f32_e32 v32, v32
	v_exp_f32_e32 v33, v33
	v_exp_f32_e32 v34, v34
	v_exp_f32_e32 v35, v35
	v_exp_f32_e32 v36, v36
	v_exp_f32_e32 v37, v37
	v_exp_f32_e32 v38, v38
	v_mfma_f32_32x32x16_bf16 v[0:15], v[232:235], v[56:59], v[0:15]
	v_exp_f32_e32 v39, v39
	v_add_f32_e32 v208, v32, v208
	v_add_f32_e32 v209, v33, v209
	v_add_f32_e32 v208, v34, v208
	v_add_f32_e32 v209, v35, v209
	v_add_f32_e32 v208, v36, v208
	v_add_f32_e32 v209, v37, v209
	v_add_f32_e32 v208, v38, v208
	v_add_f32_e32 v209, v39, v209
	v_cvt_pk_bf16_f32 v52, v32, v33
	v_cvt_pk_bf16_f32 v53, v34, v35
	v_cvt_pk_bf16_f32 v54, v36, v37
	v_cvt_pk_bf16_f32 v55, v38, v39
	v_fma_f32 v40, v40, s28, -v166
	v_fma_f32 v41, v41, s28, -v166
	v_fma_f32 v42, v42, s28, -v166
	s_waitcnt lgkmcnt(0)
	v_mfma_f32_32x32x16_bf16 v[16:31], v[236:239], v[52:55], v[16:31]
	v_fma_f32 v43, v43, s28, -v166
	v_fma_f32 v44, v44, s28, -v166
	v_fma_f32 v45, v45, s28, -v166
	v_fma_f32 v46, v46, s28, -v166
	v_fma_f32 v47, v47, s28, -v166
	v_exp_f32_e32 v40, v40
	v_exp_f32_e32 v41, v41
	v_exp_f32_e32 v42, v42
	v_exp_f32_e32 v43, v43
	v_exp_f32_e32 v44, v44
	v_exp_f32_e32 v45, v45
	v_exp_f32_e32 v46, v46
	v_mfma_f32_32x32x16_bf16 v[0:15], v[240:243], v[52:55], v[0:15]
	v_exp_f32_e32 v47, v47
	v_add_f32_e32 v208, v40, v208
	v_add_f32_e32 v209, v41, v209
	v_add_f32_e32 v208, v42, v208
	v_add_f32_e32 v209, v43, v209
	v_add_f32_e32 v208, v44, v208
	v_add_f32_e32 v209, v45, v209
	v_add_f32_e32 v208, v46, v208
	v_add_f32_e32 v209, v47, v209
	v_cvt_pk_bf16_f32 v32, v40, v41
	v_cvt_pk_bf16_f32 v33, v42, v43
	v_cvt_pk_bf16_f32 v34, v44, v45
	v_cvt_pk_bf16_f32 v35, v46, v47
	v_add_f32_e32 v211, v208, v209
	v_add_f32_e32 v200, v212, v211
	v_mfma_f32_32x32x16_bf16 v[16:31], v[244:247], v[32:35], v[16:31]
	s_addk_i32 s19, 0xff80
	v_add_u32_e32 v197, 0x80, v197
	s_addk_i32 s18, 0x80
	v_mfma_f32_32x32x16_bf16 v[0:15], v[248:251], v[32:35], v[0:15]
	s_andn2_b64 vcc, exec, s[6:7]
	s_cbranch_vccz .LBB0_828
	s_mov_b32 s21, s20
	s_branch .LBB0_814
